# comb12 + final-norm gains loaded once + gMLP statistics table built cooperatively by all 8 waves
# baseline (speedup 1.0000x reference)
; #define LAS __attribute__((address_space(3)))
; #define KIN(i) (*(const float* const __attribute__((address_space(4)))*)(kp + kz + 8 * (i)))
; __global__ void __launch_bounds__(NTHR, 2) fwd_megakernel(Args args) {
;     ...
;             const int tc0 = (su >> 2) * 128, qi = su & 3, i0 = 32 * qi, J = qi < 2 ? 64 : 128;
;             constexpr int LDB = 136;
;             LAS bf16_t* Bt = (LAS bf16_t*)lds;
;             LAS f32x2* st = (LAS f32x2*)(lds + 2 * 128 * LDB * 2);
;             LAS float* red = (LAS float*)(lds + 2 * 128 * LDB * 2 + 1024);
;             if (tid < J) { const f32x4* p = (const f32x4*)(VSTAT + (size_t)(tc0 + tid) * 32); float s1 = 0.f, s2 = 0.f;
; #pragma unroll
;                 for (int j = 0; j < 8; ++j) { const f32x4 v = p[j]; s1 += v[0] + v[2]; s2 += v[1] + v[3]; }
;                 const float mean = s1 * (1.0f / CCH), var = fmaxf(s2 * (1.0f / CCH) - mean * mean, 0.f); st[tid] = (f32x2){mean, rsqrtf(var + LN_EPS)}; }
;             const int mb = wave & 1, nq = wave >> 1, fr = lane & 15, fq = lane >> 4;
;             const int trow = tc0 + i0 + 16 * mb + fr;
;             const float* lng = KIN(I_SGU_LN_G); const float* lnb = KIN(I_SGU_LN_B); const float* sgb = KIN(I_SGU_B);
;             const int c8 = tid & 15, jb = tid >> 4, nk = J / 32;
;             u32x4 pv[4]; f32x4 pg0, pg1, pb0, pb1; bf16x8 pw[4]; u32x2 pu0, pu1; float pbs;
.LBB0_659:
	global_load_dwordx4 v[240:243], v[212:213], off
	global_load_dwordx4 v[244:247], v[214:215], off
	s_and_b32 s11, s23, 0xffffff80
	s_and_b32 s44, s58, 3
	v_lshrrev_b32_e32 v218, 4, v221
	v_lshl_or_b32 v218, s44, 5, v218
	v_and_b32_e32 v219, 15, v221
	v_lshlrev_b32_e32 v219, 4, v219
	v_lshl_add_u32 v218, v218, 8, v219
	v_mov_b32_e32 v219, 0
	s_add_u32 s100, s14, 0xbc08000
	s_addc_u32 s101, s15, 0
	v_lshl_add_u64 v[218:219], s[100:101], 0, v[218:219]
	s_mov_b64 s[100:101], 0x8000
	s_cmp_gt_u32 s44, 1
	s_cselect_b64 s[26:27], -1, 0
	s_and_b64 s[4:5], s[26:27], exec
	s_cselect_b32 s4, 0x80, 64
	v_lshrrev_b32_e32 v248, 2, v220
	s_lshl_b32 s96, s95, 4
	s_add_i32 s96, s96, s11
	v_add_u32_e32 v248, s96, v248
	v_and_b32_e32 v249, 3, v220
	v_lshlrev_b32_e32 v249, 5, v249
	v_lshl_add_u32 v248, v248, 7, v249
	global_load_dwordx4 v[230:233], v248, s[38:39]
	global_load_dwordx4 v[234:237], v248, s[38:39] offset:16
.LBB0_661:
	s_nop 0
	v_or_b32_e32 v146, s11, v163
	v_ashrrev_i32_e32 v147, 31, v146
	v_lshlrev_b64 v[8:9], 11, v[146:147]
	v_lshl_add_u64 v[112:113], v[122:123], 0, v[8:9]
	v_add_co_u32_e32 v8, vcc, 0x10000, v112
	v_or_b32_e32 v152, 64, v146
	s_nop 0
	v_addc_co_u32_e32 v9, vcc, 0, v113, vcc
	global_load_dwordx4 v[44:47], v[112:113], off
	global_load_dwordx4 v[40:43], v[8:9], off
	v_cndmask_b32_e64 v8, 0, 1, s[26:27]
	v_cmp_ne_u32_e64 s[4:5], 1, v8
	s_andn2_b64 vcc, exec, s[26:27]
	v_ashrrev_i32_e32 v153, 31, v152
	s_cbranch_vccnz .LBB0_663
	v_lshlrev_b64 v[0:1], 11, v[152:153]
	v_lshl_add_u64 v[0:1], v[122:123], 0, v[0:1]
	global_load_dwordx4 v[0:3], v[0:1], off

; #define LAS __attribute__((address_space(3)))
; __device__ __forceinline__ unsigned cvt_pk_bf16(float lo, float hi) { unsigned r; asm volatile("v_cvt_pk_bf16_f32 %0, %1, %2" : "=v"(r) : "v"(lo), "v"(hi)); return r; }
; __device__ __forceinline__ float bf_lo(unsigned u) { return __uint_as_float(u << 16); }
; __device__ __forceinline__ float bf_hi(unsigned u) { return __uint_as_float(u & 0xffff0000u); }
; __global__ void __launch_bounds__(NTHR, 2) fwd_megakernel(Args args) {
;     ...
;             if (tid < J) { const f32x4* p = (const f32x4*)(VSTAT + (size_t)(tc0 + tid) * 32); float s1 = 0.f, s2 = 0.f;
; #pragma unroll
;                 for (int j = 0; j < 8; ++j) { const f32x4 v = p[j]; s1 += v[0] + v[2]; s2 += v[1] + v[3]; }
;                 const float mean = s1 * (1.0f / CCH), var = fmaxf(s2 * (1.0f / CCH) - mean * mean, 0.f); st[tid] = (f32x2){mean, rsqrtf(var + LN_EPS)}; }
;     ...
;                 LAS bf16_t* Bc = Bt + (h & 1) * (128 * LDB);
; #pragma unroll
;                 for (int k = 0; k < 4; ++k) if (k < nk) { const int j = jb + 32 * k; const u32x4 v = pv[k]; const f32x2 ms = st[j];
;                     const f32x4 x0 = (f32x4){bf_lo(v.x), bf_hi(v.x), bf_lo(v.y), bf_hi(v.y)}, x1 = (f32x4){bf_lo(v.z), bf_hi(v.z), bf_lo(v.w), bf_hi(v.w)};
;                     const f32x4 y0 = (x0 - ms.x) * ms.y * pg0 + pb0, y1 = (x1 - ms.x) * ms.y * pg1 + pb1;
;                     LAS bf16_t* d = Bc + (c8 * 8) * LDB + (j ^ (8 * c8));
;                     const unsigned p0 = cvt_pk_bf16(y0[0], y0[1]), p1 = cvt_pk_bf16(y0[2], y0[3]), p2 = cvt_pk_bf16(y1[0], y1[1]), p3 = cvt_pk_bf16(y1[2], y1[3]);
;                     d[0 * LDB] = (bf16_t)(p0 & 0xffffu); d[1 * LDB] = (bf16_t)(p0 >> 16); d[2 * LDB] = (bf16_t)(p1 & 0xffffu); d[3 * LDB] = (bf16_t)(p1 >> 16);
;                     d[4 * LDB] = (bf16_t)(p2 & 0xffffu); d[5 * LDB] = (bf16_t)(p2 >> 16); d[6 * LDB] = (bf16_t)(p3 & 0xffffu); d[7 * LDB] = (bf16_t)(p3 >> 16); }
.LBB0_669:
	v_or_b32_e32 v134, s11, v48
	v_ashrrev_i32_e32 v135, 31, v134
	v_lshlrev_b32_e32 v120, 2, v48
	v_add_u32_e32 v223, 0x14600, v120
	v_lshlrev_b64 v[48:49], 11, v[134:135]
	v_lshl_add_u64 v[150:151], v[130:131], 0, v[48:49]
	global_load_dword v136, v120, s[20:21]
	global_load_dwordx2 v[140:141], v[150:151], off
	global_load_dwordx2 v[138:139], v[150:151], off offset:32
	s_waitcnt vmcnt(7)
	v_pk_add_f32 v[230:231], v[230:231], v[232:233]
	v_pk_add_f32 v[234:235], v[234:235], v[236:237]
	v_pk_add_f32 v[230:231], v[230:231], v[234:235]
	s_nop 1
	v_add_f32_dpp v232, v230, v230 quad_perm:[1,0,3,2] row_mask:0xf bank_mask:0xf
	v_add_f32_dpp v233, v231, v231 quad_perm:[1,0,3,2] row_mask:0xf bank_mask:0xf
	s_nop 1
	v_add_f32_dpp v230, v232, v232 quad_perm:[2,3,0,1] row_mask:0xf bank_mask:0xf
	v_add_f32_dpp v231, v233, v233 quad_perm:[2,3,0,1] row_mask:0xf bank_mask:0xf
	s_nop 1
	v_pk_mul_f32 v[230:231], v[230:231], s[22:23] op_sel_hi:[1,0]
	s_nop 0
	v_fma_f32 v231, -v230, v230, v231
	v_max_f32_e32 v231, 0, v231
	v_add_f32_e32 v231, 0x3727c5ac, v231
	v_rsq_f32_e32 v231, v231
	v_lshrrev_b32_e32 v249, 2, v220
	s_lshl_b32 s96, s95, 7
	s_add_i32 s96, s96, 0x11000
	v_lshl_add_u32 v249, v249, 3, s96
	ds_write_b64 v249, v[230:231]
	v_lshlrev_b32_e32 v238, 4, v221
	v_add_u32_e32 v238, 0x11600, v238
	v_mov_b32_e32 v239, v221
	v_lshlrev_b32_e32 v239, 4, v239
	v_add_u32_e32 v239, 0x13600, v239
	ds_write_b128 v238, v[240:243]
	ds_write_b128 v239, v[244:247]
	s_waitcnt lgkmcnt(0)
	s_barrier
	ds_read_b128 v[16:19], v203 offset:16
	ds_read_b128 v[24:27], v203
	ds_read_b128 v[20:23], v203 offset:4112
	ds_read_b128 v[28:31], v203 offset:4096
	ds_read_b64 v[48:49], v181
	s_waitcnt vmcnt(6)
	v_lshlrev_b32_e32 v50, 16, v44
	v_and_b32_e32 v51, 0xffff0000, v44
	v_lshlrev_b32_e32 v44, 16, v45
	v_and_b32_e32 v45, 0xffff0000, v45
	v_lshlrev_b32_e32 v52, 16, v46
	v_and_b32_e32 v53, 0xffff0000, v46
	v_lshlrev_b32_e32 v54, 16, v47
	v_and_b32_e32 v55, 0xffff0000, v47
	s_waitcnt lgkmcnt(0)
	v_sub_f32_e32 v47, v51, v48
	v_sub_f32_e32 v46, v50, v48
	v_sub_f32_e32 v45, v45, v48
	v_sub_f32_e32 v44, v44, v48
	v_pk_mul_f32 v[46:47], v[48:49], v[46:47] op_sel:[1,0]
	v_pk_mul_f32 v[44:45], v[48:49], v[44:45] op_sel:[1,0]
	s_waitcnt vmcnt(5)
	v_pk_fma_f32 v[46:47], v[24:25], v[46:47], v[28:29]
	v_sub_f32_e32 v51, v55, v48
	v_sub_f32_e32 v50, v54, v48
	v_sub_f32_e32 v53, v53, v48
	v_sub_f32_e32 v52, v52, v48
	v_pk_fma_f32 v[44:45], v[26:27], v[44:45], v[30:31]
	v_pk_mul_f32 v[52:53], v[48:49], v[52:53] op_sel:[1,0]
	v_pk_mul_f32 v[48:49], v[48:49], v[50:51] op_sel:[1,0]
	v_cvt_pk_bf16_f32 v46, v46, v47
	v_pk_fma_f32 v[50:51], v[16:17], v[52:53], v[20:21]
	v_pk_fma_f32 v[48:49], v[18:19], v[48:49], v[22:23]
	v_cvt_pk_bf16_f32 v44, v44, v45
	v_cvt_pk_bf16_f32 v45, v50, v51
	v_lshlrev_b32_e32 v50, 16, v43
	v_cvt_pk_bf16_f32 v47, v48, v49
	ds_write_b16 v186, v46
	ds_write_b16_d16_hi v186, v46 offset:272
	ds_write_b16 v186, v44 offset:544
	ds_write_b16_d16_hi v186, v44 offset:816
	ds_write_b16 v186, v45 offset:1088
	ds_write_b16_d16_hi v186, v45 offset:1360
	ds_write_b16 v186, v47 offset:1632
	ds_write_b16_d16_hi v186, v47 offset:1904
	ds_read_b64 v[44:45], v187
	v_lshlrev_b32_e32 v46, 16, v40
	v_and_b32_e32 v47, 0xffff0000, v40
	v_lshlrev_b32_e32 v40, 16, v41
	v_and_b32_e32 v41, 0xffff0000, v41
	v_lshlrev_b32_e32 v48, 16, v42
	v_and_b32_e32 v49, 0xffff0000, v42
	v_and_b32_e32 v51, 0xffff0000, v43
	s_waitcnt lgkmcnt(0)
	v_sub_f32_e32 v43, v47, v44
	v_sub_f32_e32 v42, v46, v44
	v_sub_f32_e32 v41, v41, v44
	v_sub_f32_e32 v40, v40, v44
	v_pk_mul_f32 v[42:43], v[44:45], v[42:43] op_sel:[1,0]
	v_pk_mul_f32 v[40:41], v[44:45], v[40:41] op_sel:[1,0]
	v_pk_fma_f32 v[42:43], v[24:25], v[42:43], v[28:29]
	v_sub_f32_e32 v47, v51, v44
	v_sub_f32_e32 v46, v50, v44
	v_sub_f32_e32 v49, v49, v44
	v_sub_f32_e32 v48, v48, v44
	v_pk_fma_f32 v[40:41], v[26:27], v[40:41], v[30:31]
	v_pk_mul_f32 v[48:49], v[44:45], v[48:49] op_sel:[1,0]
	v_pk_mul_f32 v[44:45], v[44:45], v[46:47] op_sel:[1,0]
	v_cvt_pk_bf16_f32 v42, v42, v43
	s_and_b64 vcc, exec, s[4:5]
	v_pk_fma_f32 v[44:45], v[18:19], v[44:45], v[22:23]
	v_pk_fma_f32 v[46:47], v[16:17], v[48:49], v[20:21]
	v_cvt_pk_bf16_f32 v40, v40, v41
	s_nop 0
	v_cvt_pk_bf16_f32 v41, v46, v47
	v_cvt_pk_bf16_f32 v43, v44, v45
	ds_write_b16 v188, v42
	ds_write_b16_d16_hi v188, v42 offset:272
	ds_write_b16 v188, v40 offset:544
	ds_write_b16_d16_hi v188, v40 offset:816
	ds_write_b16 v188, v41 offset:1088
	ds_write_b16_d16_hi v188, v41 offset:1360
	ds_write_b16 v188, v43 offset:1632
	ds_write_b16_d16_hi v188, v43 offset:1904
	s_cbranch_vccnz .LBB0_671
; #define LAS __attribute__((address_space(3)))
; __device__ __forceinline__ unsigned cvt_pk_bf16(float lo, float hi) { unsigned r; asm volatile("v_cvt_pk_bf16_f32 %0, %1, %2" : "=v"(r) : "v"(lo), "v"(hi)); return r; }
; __device__ __forceinline__ float bf_lo(unsigned u) { return __uint_as_float(u << 16); }
; __device__ __forceinline__ float bf_hi(unsigned u) { return __uint_as_float(u & 0xffff0000u); }
; __global__ void __launch_bounds__(NTHR, 2) fwd_megakernel(Args args) {
;     ...
;                 for (int k = 0; k < 4; ++k) if (k < nk) { const int j = jb + 32 * k; const u32x4 v = pv[k]; const f32x2 ms = st[j];
;                     const f32x4 x0 = (f32x4){bf_lo(v.x), bf_hi(v.x), bf_lo(v.y), bf_hi(v.y)}, x1 = (f32x4){bf_lo(v.z), bf_hi(v.z), bf_lo(v.w), bf_hi(v.w)};
;                     const f32x4 y0 = (x0 - ms.x) * ms.y * pg0 + pb0, y1 = (x1 - ms.x) * ms.y * pg1 + pb1;
;                     LAS bf16_t* d = Bc + (c8 * 8) * LDB + (j ^ (8 * c8));
;                     const unsigned p0 = cvt_pk_bf16(y0[0], y0[1]), p1 = cvt_pk_bf16(y0[2], y0[3]), p2 = cvt_pk_bf16(y1[0], y1[1]), p3 = cvt_pk_bf16(y1[2], y1[3]);
;                     d[0 * LDB] = (bf16_t)(p0 & 0xffffu); d[1 * LDB] = (bf16_t)(p0 >> 16); d[2 * LDB] = (bf16_t)(p1 & 0xffffu); d[3 * LDB] = (bf16_t)(p1 >> 16);
;                     d[4 * LDB] = (bf16_t)(p2 & 0xffffu); d[5 * LDB] = (bf16_t)(p2 >> 16); d[6 * LDB] = (bf16_t)(p3 & 0xffffu); d[7 * LDB] = (bf16_t)(p3 >> 16); }
	ds_read_b64 v[40:41], v189
	v_lshlrev_b32_e32 v44, 16, v0
	v_and_b32_e32 v45, 0xffff0000, v0
	v_lshlrev_b32_e32 v42, 16, v1
	v_and_b32_e32 v43, 0xffff0000, v1
	v_lshlrev_b32_e32 v48, 16, v2
	v_and_b32_e32 v49, 0xffff0000, v2
	v_lshlrev_b32_e32 v46, 16, v3
	v_and_b32_e32 v47, 0xffff0000, v3
	s_waitcnt lgkmcnt(0)
	v_sub_f32_e32 v45, v45, v40
	v_sub_f32_e32 v44, v44, v40
	v_sub_f32_e32 v43, v43, v40
	v_sub_f32_e32 v42, v42, v40
	v_pk_mul_f32 v[44:45], v[40:41], v[44:45] op_sel:[1,0]
	v_sub_f32_e32 v47, v47, v40
	v_sub_f32_e32 v46, v46, v40
	v_sub_f32_e32 v49, v49, v40
	v_sub_f32_e32 v48, v48, v40
	v_pk_mul_f32 v[42:43], v[40:41], v[42:43] op_sel:[1,0]
	v_pk_fma_f32 v[44:45], v[24:25], v[44:45], v[28:29]
	v_pk_mul_f32 v[48:49], v[40:41], v[48:49] op_sel:[1,0]
	v_pk_mul_f32 v[40:41], v[40:41], v[46:47] op_sel:[1,0]
	v_pk_fma_f32 v[42:43], v[26:27], v[42:43], v[30:31]
	v_pk_fma_f32 v[40:41], v[18:19], v[40:41], v[22:23]
	v_cvt_pk_bf16_f32 v44, v44, v45
	v_pk_fma_f32 v[46:47], v[16:17], v[48:49], v[20:21]
	v_cvt_pk_bf16_f32 v42, v42, v43
	v_and_b32_e32 v45, 0xffff0000, v4
	v_cvt_pk_bf16_f32 v43, v46, v47
	v_cvt_pk_bf16_f32 v40, v40, v41
	ds_write_b16 v190, v44
	ds_write_b16_d16_hi v190, v44 offset:272
	ds_write_b16 v190, v42 offset:544
	ds_write_b16_d16_hi v190, v42 offset:816
	ds_write_b16 v190, v43 offset:1088
	ds_write_b16_d16_hi v190, v43 offset:1360
	ds_write_b16 v190, v40 offset:1632
	ds_write_b16_d16_hi v190, v40 offset:1904
	ds_read_b64 v[40:41], v191
	v_lshlrev_b32_e32 v42, 16, v5
	v_and_b32_e32 v43, 0xffff0000, v5
	v_lshlrev_b32_e32 v44, 16, v4
	v_lshlrev_b32_e32 v46, 16, v6
	s_waitcnt lgkmcnt(0)
	v_sub_f32_e32 v43, v43, v40
	v_sub_f32_e32 v42, v42, v40
	v_and_b32_e32 v47, 0xffff0000, v6
	v_sub_f32_e32 v45, v45, v40
	v_sub_f32_e32 v44, v44, v40
	v_pk_mul_f32 v[42:43], v[40:41], v[42:43] op_sel:[1,0]
	v_lshlrev_b32_e32 v48, 16, v7
	v_and_b32_e32 v49, 0xffff0000, v7
	v_pk_mul_f32 v[44:45], v[40:41], v[44:45] op_sel:[1,0]
	v_pk_fma_f32 v[26:27], v[26:27], v[42:43], v[30:31]
	v_sub_f32_e32 v31, v47, v40
	v_sub_f32_e32 v30, v46, v40
	v_pk_fma_f32 v[24:25], v[24:25], v[44:45], v[28:29]
	v_sub_f32_e32 v29, v49, v40
	v_sub_f32_e32 v28, v48, v40
	v_pk_mul_f32 v[30:31], v[40:41], v[30:31] op_sel:[1,0]
	v_pk_mul_f32 v[28:29], v[40:41], v[28:29] op_sel:[1,0]
	v_pk_fma_f32 v[16:17], v[16:17], v[30:31], v[20:21]
	v_cvt_pk_bf16_f32 v20, v24, v25
	v_pk_fma_f32 v[18:19], v[18:19], v[28:29], v[22:23]
	v_cvt_pk_bf16_f32 v21, v26, v27
	v_cvt_pk_bf16_f32 v16, v16, v17
	s_nop 0
	v_cvt_pk_bf16_f32 v17, v18, v19
	ds_write_b16 v192, v20
	ds_write_b16_d16_hi v192, v20 offset:272
	ds_write_b16 v192, v21 offset:544
	ds_write_b16_d16_hi v192, v21 offset:816
	ds_write_b16 v192, v16 offset:1088
	ds_write_b16_d16_hi v192, v16 offset:1360
	ds_write_b16 v192, v17 offset:1632
	ds_write_b16_d16_hi v192, v17 offset:1904
